# P3 weight-copy items: the vmcnt(0) between the first and last four row loads moved to the first consumer as vmcnt(4) (one memory round trip per item instead of two)
# speedup vs baseline: 1.0026x; 1.0026x over previous
; #define LAS __attribute__((address_space(3)))
; __device__ __forceinline__ unsigned cvtpk(float lo, float hi) { f32x2 v = {lo, hi}; bf16x2_t b = __builtin_convertvector(v, bf16x2_t); return __builtin_bit_cast(unsigned, b); }
; __device__ __forceinline__ void tr_item(const float* __restrict__ W, int ldw, int K, bf16* __restrict__ WT, int nblk, int mapmode, const float* __restrict__ ksc, LAS float* scr, int item, int lane) {
;     const int kb = item / nblk, nb = item - kb * nblk, k0 = 64 * kb, n0 = 32 * nb;
;     const int L = (n0 & ~255) + 64 * ((n0 >> 5) & 3) + 32 * ((n0 >> 7) & 1);
;     const int src0 = mapmode ? ((L >> 5) & 1) * DFF + 128 * (L >> 8) + 32 * ((L >> 6) & 3) : L;
;     f32x4 v[8];
; #pragma unroll
;     for (int i = 0; i < 8; ++i) { const int kk = 8 * i + (lane >> 3); v[i] = __builtin_nontemporal_load((const f32x4*)(W + (size_t)(k0 + kk) * ldw + src0 + 4 * (lane & 7))); }
; #pragma unroll
;     for (int i = 0; i < 8; ++i) { const int kk = 8 * i + (lane >> 3); f32x4 w = v[i]; if (ksc) w *= ksc[k0 + kk];
;         LAS float* d = scr + kk * 33 + 4 * (lane & 7); d[0] = w[0]; d[1] = w[1]; d[2] = w[2]; d[3] = w[3]; }
;     asm volatile("s_waitcnt lgkmcnt(0)" ::: "memory");
;     const int c = lane & 7;
; #pragma unroll
;     for (int j = 0; j < 4; ++j) { const int n = (lane >> 3) + 8 * j; const LAS float* s = scr + (8 * c) * 33 + n;
;         u32x4 o; o.x = cvtpk(s[0 * 33], s[1 * 33]); o.y = cvtpk(s[2 * 33], s[3 * 33]); o.z = cvtpk(s[4 * 33], s[5 * 33]); o.w = cvtpk(s[6 * 33], s[7 * 33]);
;         *(u32x4*)(WT + (size_t)(n0 + n) * K + k0 + 8 * c) = o; }
;     asm volatile("s_waitcnt lgkmcnt(0)" ::: "memory");
; }
.LBB0_518:
	s_cmpk_gt_i32 s28, 0x7f
	s_mov_b64 s[4:5], -1
	s_cbranch_scc0 .LBB0_552
	s_cmpk_gt_u32 s28, 0x17f
	s_cbranch_scc0 .LBB0_549
	s_cmpk_gt_u32 s28, 0x27f
	s_cbranch_scc0 .LBB0_546
	s_cmpk_gt_u32 s28, 0x47f
	s_cbranch_scc0 .LBB0_543
	s_cmpk_gt_u32 s28, 0xf7f
	s_cbranch_scc0 .LBB0_524
	s_mov_b64 s[4:5], s[0:1]
	s_load_dwordx2 s[4:5], s[4:5], 0xe0
	s_lshl_b32 s22, s28, 5
	s_lshl_b32 s25, s28, 3
	s_and_b32 s23, s22, 0x3e0
	s_lshl_b32 s24, s28, 6
	s_and_b32 s25, s25, 32
	s_and_b32 s22, s22, 0x300
	s_and_b32 s24, s24, 0xc0
	s_or_b32 s22, s25, s22
	s_and_b32 s6, s37, 0x7fffffc0
	s_or_b32 s22, s22, s24
	s_addk_i32 s6, 0xe100
	s_lshl_b32 s22, s22, 2
	s_waitcnt lgkmcnt(0)
	s_add_u32 s4, s4, s22
	v_or_b32_e32 v4, s6, v1
	s_addc_u32 s5, s5, 0
	v_lshl_add_u64 v[2:3], s[4:5], 0, v[38:39]
	v_lshlrev_b32_e32 v4, 10, v4
	v_mov_b32_e32 v5, v39
	v_lshl_add_u64 v[30:31], v[4:5], 2, v[2:3]
	v_add_co_u32_e32 v6, vcc, s44, v30
	s_mov_b64 s[20:21], s[0:1]
	s_nop 0
	v_addc_co_u32_e32 v7, vcc, 0, v31, vcc
	v_add_co_u32_e32 v10, vcc, s45, v30
	global_load_dwordx4 v[2:5], v[30:31], off nt
	s_nop 0
	global_load_dwordx4 v[6:9], v[6:7], off nt
	v_addc_co_u32_e32 v11, vcc, 0, v31, vcc
	v_add_co_u32_e32 v14, vcc, s46, v30
	v_mov_b32_e32 v41, v39
	s_nop 0
	v_addc_co_u32_e32 v15, vcc, 0, v31, vcc
	v_add_co_u32_e32 v18, vcc, s47, v30
	global_load_dwordx4 v[10:13], v[10:11], off nt
	s_nop 0
	global_load_dwordx4 v[14:17], v[14:15], off nt
	v_addc_co_u32_e32 v19, vcc, 0, v31, vcc
	v_add_co_u32_e32 v22, vcc, s48, v30
	v_or_b32_e32 v34, s23, v1
	s_nop 0
	v_addc_co_u32_e32 v23, vcc, 0, v31, vcc
	global_load_dwordx4 v[18:21], v[18:19], off nt
	s_nop 0
	global_load_dwordx4 v[22:25], v[22:23], off nt
	v_add_co_u32_e32 v26, vcc, s49, v30
	s_load_dwordx2 s[4:5], s[20:21], 0xf0
	s_nop 0
	v_addc_co_u32_e32 v27, vcc, 0, v31, vcc
	global_load_dwordx4 v[26:29], v[26:27], off nt
	v_add_co_u32_e32 v30, vcc, s50, v30
	s_lshl_b64 s[20:21], s[6:7], 1
	s_nop 0
	v_addc_co_u32_e32 v31, vcc, 0, v31, vcc
	global_load_dwordx4 v[30:33], v[30:31], off nt
	s_waitcnt lgkmcnt(0)
	s_add_u32 s4, s4, s20
	s_addc_u32 s5, s5, s21
	v_lshl_add_u64 v[36:37], s[4:5], 0, v[40:41]
	v_mov_b32_e32 v35, v39
	v_mul_u32_u24_e32 v34, 0x1600, v34
	v_lshl_add_u64 v[36:37], v[36:37], 0, s[8:9]
	s_mov_b64 s[4:5], 0
	s_waitcnt vmcnt(4)
	ds_write2_b32 v51, v2, v3 offset1:1
	ds_write2_b32 v51, v4, v5 offset0:2 offset1:3
	ds_write2_b32 v52, v6, v7 offset1:1
	ds_write2_b32 v53, v8, v9 offset1:1
	ds_write2_b32 v54, v10, v11 offset1:1
	ds_write2_b32 v55, v12, v13 offset1:1
	ds_write2_b32 v56, v14, v15 offset1:1
	ds_write2_b32 v57, v16, v17 offset1:1
	s_waitcnt vmcnt(3)
	ds_write2_b32 v58, v18, v19 offset1:1
	ds_write2_b32 v59, v20, v21 offset1:1
	s_waitcnt vmcnt(2)
	ds_write2_b32 v60, v22, v23 offset1:1
	ds_write2_b32 v61, v24, v25 offset1:1
	s_waitcnt vmcnt(1)
	ds_write2_b32 v62, v26, v27 offset1:1
	ds_write2_b32 v63, v28, v29 offset1:1
	s_waitcnt vmcnt(0)
	ds_write2_b32 v64, v30, v31 offset1:1
	ds_write2_b32 v65, v32, v33 offset1:1
	s_waitcnt lgkmcnt(0)
	ds_read2_b32 v[6:7], v49 offset0:33 offset1:41
	ds_read2_b32 v[8:9], v49 offset1:8
	ds_read2_b32 v[10:11], v49 offset0:66 offset1:74
	ds_read2_b32 v[12:13], v49 offset0:99 offset1:107
	ds_read2_b32 v[14:15], v49 offset0:132 offset1:140
	ds_read2_b32 v[16:17], v49 offset0:165 offset1:173
	ds_read2_b32 v[18:19], v49 offset0:198 offset1:206
	ds_read2_b32 v[20:21], v49 offset0:231 offset1:239
	v_lshl_add_u64 v[22:23], v[36:37], 0, v[34:35]
	s_waitcnt lgkmcnt(6)
	v_cvt_pk_bf16_f32 v2, v8, v6
	s_waitcnt lgkmcnt(4)
	v_cvt_pk_bf16_f32 v3, v10, v12
	s_waitcnt lgkmcnt(2)
	v_cvt_pk_bf16_f32 v4, v14, v16
	s_waitcnt lgkmcnt(0)
	v_cvt_pk_bf16_f32 v5, v18, v20
	global_store_dwordx4 v[22:23], v[2:5], off
	v_or_b32_e32 v6, s23, v46
	v_mul_u32_u24_e32 v6, 0x1600, v6
	v_cvt_pk_bf16_f32 v2, v9, v7
	v_cvt_pk_bf16_f32 v3, v11, v13
	v_cvt_pk_bf16_f32 v4, v15, v17
	v_cvt_pk_bf16_f32 v5, v19, v21
	ds_read2_b32 v[8:9], v49 offset0:16 offset1:24
	ds_read2_b32 v[10:11], v49 offset0:49 offset1:57
	ds_read2_b32 v[12:13], v49 offset0:82 offset1:90
	ds_read2_b32 v[14:15], v49 offset0:115 offset1:123
	ds_read2_b32 v[16:17], v49 offset0:148 offset1:156
	ds_read2_b32 v[18:19], v49 offset0:181 offset1:189
	ds_read2_b32 v[20:21], v49 offset0:214 offset1:222
	ds_read2_b32 v[22:23], v49 offset0:247 offset1:255
	v_mov_b32_e32 v7, v39
	v_lshl_add_u64 v[6:7], v[36:37], 0, v[6:7]
	global_store_dwordx4 v[6:7], v[2:5], off
	v_or_b32_e32 v6, s23, v47
	v_mul_u32_u24_e32 v6, 0x1600, v6
	v_mov_b32_e32 v7, v39
	s_waitcnt lgkmcnt(6)
	v_cvt_pk_bf16_f32 v2, v8, v10
	s_waitcnt lgkmcnt(4)
	v_cvt_pk_bf16_f32 v3, v12, v14
	s_waitcnt lgkmcnt(2)
	v_cvt_pk_bf16_f32 v4, v16, v18
	s_waitcnt lgkmcnt(0)
	v_cvt_pk_bf16_f32 v5, v20, v22
	v_lshl_add_u64 v[6:7], v[36:37], 0, v[6:7]
	global_store_dwordx4 v[6:7], v[2:5], off
	v_or_b32_e32 v6, s23, v48
	v_mul_u32_u24_e32 v6, 0x1600, v6
	v_mov_b32_e32 v7, v39
	v_cvt_pk_bf16_f32 v2, v9, v11
	v_cvt_pk_bf16_f32 v3, v13, v15
	v_cvt_pk_bf16_f32 v4, v17, v19
	v_cvt_pk_bf16_f32 v5, v21, v23
	v_lshl_add_u64 v[6:7], v[36:37], 0, v[6:7]
	global_store_dwordx4 v[6:7], v[2:5], off
	s_waitcnt lgkmcnt(0)

; #define LAS __attribute__((address_space(3)))
; __device__ __forceinline__ unsigned cvtpk(float lo, float hi) { f32x2 v = {lo, hi}; bf16x2_t b = __builtin_convertvector(v, bf16x2_t); return __builtin_bit_cast(unsigned, b); }
; __device__ __forceinline__ void tr_item(const float* __restrict__ W, int ldw, int K, bf16* __restrict__ WT, int nblk, int mapmode, const float* __restrict__ ksc, LAS float* scr, int item, int lane) {
;     const int kb = item / nblk, nb = item - kb * nblk, k0 = 64 * kb, n0 = 32 * nb;
;     const int L = (n0 & ~255) + 64 * ((n0 >> 5) & 3) + 32 * ((n0 >> 7) & 1);
;     const int src0 = mapmode ? ((L >> 5) & 1) * DFF + 128 * (L >> 8) + 32 * ((L >> 6) & 3) : L;
;     f32x4 v[8];
; #pragma unroll
;     for (int i = 0; i < 8; ++i) { const int kk = 8 * i + (lane >> 3); v[i] = __builtin_nontemporal_load((const f32x4*)(W + (size_t)(k0 + kk) * ldw + src0 + 4 * (lane & 7))); }
; #pragma unroll
;     for (int i = 0; i < 8; ++i) { const int kk = 8 * i + (lane >> 3); f32x4 w = v[i]; if (ksc) w *= ksc[k0 + kk];
;         LAS float* d = scr + kk * 33 + 4 * (lane & 7); d[0] = w[0]; d[1] = w[1]; d[2] = w[2]; d[3] = w[3]; }
;     asm volatile("s_waitcnt lgkmcnt(0)" ::: "memory");
;     const int c = lane & 7;
; #pragma unroll
;     for (int j = 0; j < 4; ++j) { const int n = (lane >> 3) + 8 * j; const LAS float* s = scr + (8 * c) * 33 + n;
;         u32x4 o; o.x = cvtpk(s[0 * 33], s[1 * 33]); o.y = cvtpk(s[2 * 33], s[3 * 33]); o.z = cvtpk(s[4 * 33], s[5 * 33]); o.w = cvtpk(s[6 * 33], s[7 * 33]);
;         *(u32x4*)(WT + (size_t)(n0 + n) * K + k0 + 8 * c) = o; }
;     asm volatile("s_waitcnt lgkmcnt(0)" ::: "memory");
; }
.LBB0_543:
	s_andn2_b64 vcc, exec, s[4:5]
	s_cbranch_vccnz .LBB0_545
	s_mov_b64 s[4:5], s[0:1]
	s_load_dwordx2 s[4:5], s[4:5], 0xb8
	s_add_i32 s22, s30, s55
	s_and_b32 s23, s22, 0x3e0
	s_and_b32 s25, s33, 32
	s_and_b32 s22, s22, 0x300
	s_and_b32 s24, s35, 0xc0
	s_or_b32 s22, s25, s22
	s_and_b32 s6, s37, 0xfc0
	s_or_b32 s22, s22, s24
	s_addk_i32 s6, 0xfb00
	s_lshl_b32 s22, s22, 2
	s_waitcnt lgkmcnt(0)
	s_add_u32 s4, s4, s22
	v_or_b32_e32 v4, s6, v1
	s_addc_u32 s5, s5, 0
	v_lshl_add_u64 v[2:3], s[4:5], 0, v[38:39]
	v_lshlrev_b32_e32 v4, 10, v4
	v_mov_b32_e32 v5, v39
	v_lshl_add_u64 v[30:31], v[4:5], 2, v[2:3]
	v_add_co_u32_e32 v6, vcc, s44, v30
	s_mov_b64 s[20:21], s[0:1]
	s_nop 0
	v_addc_co_u32_e32 v7, vcc, 0, v31, vcc
	v_add_co_u32_e32 v10, vcc, s45, v30
	global_load_dwordx4 v[2:5], v[30:31], off nt
	s_nop 0
	global_load_dwordx4 v[6:9], v[6:7], off nt
	v_addc_co_u32_e32 v11, vcc, 0, v31, vcc
	v_add_co_u32_e32 v14, vcc, s46, v30
	v_mov_b32_e32 v41, v39
	s_nop 0
	v_addc_co_u32_e32 v15, vcc, 0, v31, vcc
	v_add_co_u32_e32 v18, vcc, s47, v30
	global_load_dwordx4 v[10:13], v[10:11], off nt
	s_nop 0
	global_load_dwordx4 v[14:17], v[14:15], off nt
	v_addc_co_u32_e32 v19, vcc, 0, v31, vcc
	v_add_co_u32_e32 v22, vcc, s48, v30
	v_or_b32_e32 v34, s23, v1
	s_nop 0
	v_addc_co_u32_e32 v23, vcc, 0, v31, vcc
	global_load_dwordx4 v[18:21], v[18:19], off nt
	s_nop 0
	global_load_dwordx4 v[22:25], v[22:23], off nt
	v_add_co_u32_e32 v26, vcc, s49, v30
	s_load_dwordx2 s[4:5], s[20:21], 0xf0
	s_nop 0
	v_addc_co_u32_e32 v27, vcc, 0, v31, vcc
	global_load_dwordx4 v[26:29], v[26:27], off nt
	v_add_co_u32_e32 v30, vcc, s50, v30
	s_lshl_b64 s[20:21], s[6:7], 1
	s_nop 0
	v_addc_co_u32_e32 v31, vcc, 0, v31, vcc
	global_load_dwordx4 v[30:33], v[30:31], off nt
	s_waitcnt lgkmcnt(0)
	s_add_u32 s4, s4, s20
	s_addc_u32 s5, s5, s21
	v_lshl_add_u64 v[36:37], s[4:5], 0, v[40:41]
	v_mov_b32_e32 v35, v39
	v_lshlrev_b32_e32 v34, 11, v34
	v_lshl_add_u64 v[36:37], v[36:37], 0, s[12:13]
	s_waitcnt vmcnt(4)
	ds_write2_b32 v51, v2, v3 offset1:1
	ds_write2_b32 v51, v4, v5 offset0:2 offset1:3
	ds_write2_b32 v52, v6, v7 offset1:1
	ds_write2_b32 v53, v8, v9 offset1:1
	ds_write2_b32 v54, v10, v11 offset1:1
	ds_write2_b32 v55, v12, v13 offset1:1
	ds_write2_b32 v56, v14, v15 offset1:1
	ds_write2_b32 v57, v16, v17 offset1:1
	s_waitcnt vmcnt(3)
	ds_write2_b32 v58, v18, v19 offset1:1
	ds_write2_b32 v59, v20, v21 offset1:1
	s_waitcnt vmcnt(2)
	ds_write2_b32 v60, v22, v23 offset1:1
	ds_write2_b32 v61, v24, v25 offset1:1
	s_waitcnt vmcnt(1)
	ds_write2_b32 v62, v26, v27 offset1:1
	ds_write2_b32 v63, v28, v29 offset1:1
	s_waitcnt vmcnt(0)
	ds_write2_b32 v64, v30, v31 offset1:1
	ds_write2_b32 v65, v32, v33 offset1:1
	s_waitcnt lgkmcnt(0)
	ds_read2_b32 v[6:7], v49 offset0:33 offset1:41
	ds_read2_b32 v[8:9], v49 offset1:8
	ds_read2_b32 v[10:11], v49 offset0:66 offset1:74
	ds_read2_b32 v[12:13], v49 offset0:99 offset1:107
	ds_read2_b32 v[14:15], v49 offset0:132 offset1:140
	ds_read2_b32 v[16:17], v49 offset0:165 offset1:173
	ds_read2_b32 v[18:19], v49 offset0:198 offset1:206
	ds_read2_b32 v[20:21], v49 offset0:231 offset1:239
	v_lshl_add_u64 v[22:23], v[36:37], 0, v[34:35]
	s_waitcnt lgkmcnt(6)
	v_cvt_pk_bf16_f32 v2, v8, v6
	s_waitcnt lgkmcnt(4)
	v_cvt_pk_bf16_f32 v3, v10, v12
	s_waitcnt lgkmcnt(2)
	v_cvt_pk_bf16_f32 v4, v14, v16
	s_waitcnt lgkmcnt(0)
	v_cvt_pk_bf16_f32 v5, v18, v20
	global_store_dwordx4 v[22:23], v[2:5], off
	v_cvt_pk_bf16_f32 v6, v9, v7
	v_cvt_pk_bf16_f32 v7, v11, v13
	v_cvt_pk_bf16_f32 v8, v15, v17
	v_cvt_pk_bf16_f32 v9, v19, v21
	v_or_b32_e32 v2, s23, v46
	ds_read2_b32 v[10:11], v49 offset0:49 offset1:57
	ds_read2_b32 v[12:13], v49 offset0:16 offset1:24
	ds_read2_b32 v[14:15], v49 offset0:82 offset1:90
	ds_read2_b32 v[16:17], v49 offset0:115 offset1:123
	ds_read2_b32 v[18:19], v49 offset0:148 offset1:156
	ds_read2_b32 v[20:21], v49 offset0:181 offset1:189
	ds_read2_b32 v[22:23], v49 offset0:214 offset1:222
	ds_read2_b32 v[24:25], v49 offset0:247 offset1:255
	v_lshlrev_b32_e32 v2, 11, v2
	v_mov_b32_e32 v3, v39
	v_lshl_add_u64 v[2:3], v[36:37], 0, v[2:3]
	global_store_dwordx4 v[2:3], v[6:9], off
	s_waitcnt lgkmcnt(6)
	v_cvt_pk_bf16_f32 v2, v12, v10
	s_waitcnt lgkmcnt(4)
	v_cvt_pk_bf16_f32 v3, v14, v16
	v_or_b32_e32 v6, s23, v47
	v_lshlrev_b32_e32 v6, 11, v6
	v_mov_b32_e32 v7, v39
	s_waitcnt lgkmcnt(2)
	v_cvt_pk_bf16_f32 v4, v18, v20
	s_waitcnt lgkmcnt(0)
	v_cvt_pk_bf16_f32 v5, v22, v24
	v_lshl_add_u64 v[6:7], v[36:37], 0, v[6:7]
	global_store_dwordx4 v[6:7], v[2:5], off
	v_or_b32_e32 v6, s23, v48
	v_lshlrev_b32_e32 v6, 11, v6
	v_mov_b32_e32 v7, v39
	v_cvt_pk_bf16_f32 v2, v13, v11
	v_cvt_pk_bf16_f32 v3, v15, v17
	v_cvt_pk_bf16_f32 v4, v19, v21
	v_cvt_pk_bf16_f32 v5, v23, v25
	v_lshl_add_u64 v[6:7], v[36:37], 0, v[6:7]
	global_store_dwordx4 v[6:7], v[2:5], off
	s_waitcnt lgkmcnt(0)

; #define LAS __attribute__((address_space(3)))
; __device__ __forceinline__ unsigned cvtpk(float lo, float hi) { f32x2 v = {lo, hi}; bf16x2_t b = __builtin_convertvector(v, bf16x2_t); return __builtin_bit_cast(unsigned, b); }
; __device__ __forceinline__ void tr_item(const float* __restrict__ W, int ldw, int K, bf16* __restrict__ WT, int nblk, int mapmode, const float* __restrict__ ksc, LAS float* scr, int item, int lane) {
;     const int kb = item / nblk, nb = item - kb * nblk, k0 = 64 * kb, n0 = 32 * nb;
;     const int L = (n0 & ~255) + 64 * ((n0 >> 5) & 3) + 32 * ((n0 >> 7) & 1);
;     const int src0 = mapmode ? ((L >> 5) & 1) * DFF + 128 * (L >> 8) + 32 * ((L >> 6) & 3) : L;
;     f32x4 v[8];
; #pragma unroll
;     for (int i = 0; i < 8; ++i) { const int kk = 8 * i + (lane >> 3); v[i] = __builtin_nontemporal_load((const f32x4*)(W + (size_t)(k0 + kk) * ldw + src0 + 4 * (lane & 7))); }
; #pragma unroll
;     for (int i = 0; i < 8; ++i) { const int kk = 8 * i + (lane >> 3); f32x4 w = v[i]; if (ksc) w *= ksc[k0 + kk];
;         LAS float* d = scr + kk * 33 + 4 * (lane & 7); d[0] = w[0]; d[1] = w[1]; d[2] = w[2]; d[3] = w[3]; }
;     asm volatile("s_waitcnt lgkmcnt(0)" ::: "memory");
;     const int c = lane & 7;
; #pragma unroll
;     for (int j = 0; j < 4; ++j) { const int n = (lane >> 3) + 8 * j; const LAS float* s = scr + (8 * c) * 33 + n;
;         u32x4 o; o.x = cvtpk(s[0 * 33], s[1 * 33]); o.y = cvtpk(s[2 * 33], s[3 * 33]); o.z = cvtpk(s[4 * 33], s[5 * 33]); o.w = cvtpk(s[6 * 33], s[7 * 33]);
;         *(u32x4*)(WT + (size_t)(n0 + n) * K + k0 + 8 * c) = o; }
;     asm volatile("s_waitcnt lgkmcnt(0)" ::: "memory");
; }
.LBB0_546:
	s_andn2_b64 vcc, exec, s[4:5]
	s_cbranch_vccnz .LBB0_548
	s_mov_b64 s[4:5], s[0:1]
	s_load_dwordx2 s[4:5], s[4:5], 0xb0
	s_add_i32 s22, s30, s55
	s_and_b32 s23, s22, 0x3e0
	s_and_b32 s25, s33, 32
	s_and_b32 s22, s22, 0x300
	s_and_b32 s24, s35, 0xc0
	s_or_b32 s22, s25, s22
	s_and_b32 s6, s37, 0x7c0
	s_or_b32 s22, s22, s24
	s_addk_i32 s6, 0xfd00
	s_lshl_b32 s22, s22, 2
	s_waitcnt lgkmcnt(0)
	s_add_u32 s4, s4, s22
	v_or_b32_e32 v4, s6, v1
	s_addc_u32 s5, s5, 0
	v_lshl_add_u64 v[2:3], s[4:5], 0, v[38:39]
	v_lshlrev_b32_e32 v4, 10, v4
	v_mov_b32_e32 v5, v39
	v_lshl_add_u64 v[30:31], v[4:5], 2, v[2:3]
	v_add_co_u32_e32 v6, vcc, s44, v30
	s_mov_b64 s[20:21], s[0:1]
	s_nop 0
	v_addc_co_u32_e32 v7, vcc, 0, v31, vcc
	v_add_co_u32_e32 v10, vcc, s45, v30
	global_load_dwordx4 v[2:5], v[30:31], off nt
	s_nop 0
	global_load_dwordx4 v[6:9], v[6:7], off nt
	v_addc_co_u32_e32 v11, vcc, 0, v31, vcc
	v_add_co_u32_e32 v14, vcc, s46, v30
	v_mov_b32_e32 v41, v39
	s_nop 0
	v_addc_co_u32_e32 v15, vcc, 0, v31, vcc
	v_add_co_u32_e32 v18, vcc, s47, v30
	global_load_dwordx4 v[10:13], v[10:11], off nt
	s_nop 0
	global_load_dwordx4 v[14:17], v[14:15], off nt
	v_addc_co_u32_e32 v19, vcc, 0, v31, vcc
	v_add_co_u32_e32 v22, vcc, s48, v30
	v_or_b32_e32 v34, s23, v1
	s_nop 0
	v_addc_co_u32_e32 v23, vcc, 0, v31, vcc
	global_load_dwordx4 v[18:21], v[18:19], off nt
	s_nop 0
	global_load_dwordx4 v[22:25], v[22:23], off nt
	v_add_co_u32_e32 v26, vcc, s49, v30
	s_load_dwordx2 s[4:5], s[20:21], 0xf0
	s_nop 0
	v_addc_co_u32_e32 v27, vcc, 0, v31, vcc
	global_load_dwordx4 v[26:29], v[26:27], off nt
	v_add_co_u32_e32 v30, vcc, s50, v30
	s_lshl_b64 s[20:21], s[6:7], 1
	s_nop 0
	v_addc_co_u32_e32 v31, vcc, 0, v31, vcc
	global_load_dwordx4 v[30:33], v[30:31], off nt
	s_waitcnt lgkmcnt(0)
	s_add_u32 s4, s4, s20
	s_addc_u32 s5, s5, s21
	v_lshl_add_u64 v[36:37], s[4:5], 0, v[40:41]
	v_mov_b32_e32 v35, v39
	v_lshlrev_b32_e32 v34, 10, v34
	v_lshl_add_u64 v[36:37], v[36:37], 0, s[14:15]
	s_waitcnt vmcnt(4)
	ds_write2_b32 v51, v2, v3 offset1:1
	ds_write2_b32 v51, v4, v5 offset0:2 offset1:3
	ds_write2_b32 v52, v6, v7 offset1:1
	ds_write2_b32 v53, v8, v9 offset1:1
	ds_write2_b32 v54, v10, v11 offset1:1
	ds_write2_b32 v55, v12, v13 offset1:1
	ds_write2_b32 v56, v14, v15 offset1:1
	ds_write2_b32 v57, v16, v17 offset1:1
	s_waitcnt vmcnt(3)
	ds_write2_b32 v58, v18, v19 offset1:1
	ds_write2_b32 v59, v20, v21 offset1:1
	s_waitcnt vmcnt(2)
	ds_write2_b32 v60, v22, v23 offset1:1
	ds_write2_b32 v61, v24, v25 offset1:1
	s_waitcnt vmcnt(1)
	ds_write2_b32 v62, v26, v27 offset1:1
	ds_write2_b32 v63, v28, v29 offset1:1
	s_waitcnt vmcnt(0)
	ds_write2_b32 v64, v30, v31 offset1:1
	ds_write2_b32 v65, v32, v33 offset1:1
	s_waitcnt lgkmcnt(0)
	ds_read2_b32 v[6:7], v49 offset0:33 offset1:41
	ds_read2_b32 v[8:9], v49 offset1:8
	ds_read2_b32 v[10:11], v49 offset0:66 offset1:74
	ds_read2_b32 v[12:13], v49 offset0:99 offset1:107
	ds_read2_b32 v[14:15], v49 offset0:132 offset1:140
	ds_read2_b32 v[16:17], v49 offset0:165 offset1:173
	ds_read2_b32 v[18:19], v49 offset0:198 offset1:206
	ds_read2_b32 v[20:21], v49 offset0:231 offset1:239
	v_lshl_add_u64 v[22:23], v[36:37], 0, v[34:35]
	s_waitcnt lgkmcnt(6)
	v_cvt_pk_bf16_f32 v2, v8, v6
	s_waitcnt lgkmcnt(4)
	v_cvt_pk_bf16_f32 v3, v10, v12
	s_waitcnt lgkmcnt(2)
	v_cvt_pk_bf16_f32 v4, v14, v16
	s_waitcnt lgkmcnt(0)
	v_cvt_pk_bf16_f32 v5, v18, v20
	global_store_dwordx4 v[22:23], v[2:5], off
	v_cvt_pk_bf16_f32 v6, v9, v7
	v_cvt_pk_bf16_f32 v7, v11, v13
	v_cvt_pk_bf16_f32 v8, v15, v17
	v_cvt_pk_bf16_f32 v9, v19, v21
	v_or_b32_e32 v2, s23, v46
	ds_read2_b32 v[10:11], v49 offset0:49 offset1:57
	ds_read2_b32 v[12:13], v49 offset0:16 offset1:24
	ds_read2_b32 v[14:15], v49 offset0:82 offset1:90
	ds_read2_b32 v[16:17], v49 offset0:115 offset1:123
	ds_read2_b32 v[18:19], v49 offset0:148 offset1:156
	ds_read2_b32 v[20:21], v49 offset0:181 offset1:189
	ds_read2_b32 v[22:23], v49 offset0:214 offset1:222
	ds_read2_b32 v[24:25], v49 offset0:247 offset1:255
	v_lshlrev_b32_e32 v2, 10, v2
	v_mov_b32_e32 v3, v39
	v_lshl_add_u64 v[2:3], v[36:37], 0, v[2:3]
	global_store_dwordx4 v[2:3], v[6:9], off
	s_waitcnt lgkmcnt(6)
	v_cvt_pk_bf16_f32 v2, v12, v10
	s_waitcnt lgkmcnt(4)
	v_cvt_pk_bf16_f32 v3, v14, v16
	v_or_b32_e32 v6, s23, v47
	v_lshlrev_b32_e32 v6, 10, v6
	v_mov_b32_e32 v7, v39
	s_waitcnt lgkmcnt(2)
	v_cvt_pk_bf16_f32 v4, v18, v20
	s_waitcnt lgkmcnt(0)
	v_cvt_pk_bf16_f32 v5, v22, v24
	v_lshl_add_u64 v[6:7], v[36:37], 0, v[6:7]
	global_store_dwordx4 v[6:7], v[2:5], off
	v_or_b32_e32 v6, s23, v48
	v_lshlrev_b32_e32 v6, 10, v6
	v_mov_b32_e32 v7, v39
	v_cvt_pk_bf16_f32 v2, v13, v11
	v_cvt_pk_bf16_f32 v3, v15, v17
	v_cvt_pk_bf16_f32 v4, v19, v21
	v_cvt_pk_bf16_f32 v5, v23, v25
	v_lshl_add_u64 v[6:7], v[36:37], 0, v[6:7]
	global_store_dwordx4 v[6:7], v[2:5], off
	s_waitcnt lgkmcnt(0)

; #define LAS __attribute__((address_space(3)))
; __device__ __forceinline__ unsigned cvtpk(float lo, float hi) { f32x2 v = {lo, hi}; bf16x2_t b = __builtin_convertvector(v, bf16x2_t); return __builtin_bit_cast(unsigned, b); }
; __device__ __forceinline__ void tr_item(const float* __restrict__ W, int ldw, int K, bf16* __restrict__ WT, int nblk, int mapmode, const float* __restrict__ ksc, LAS float* scr, int item, int lane) {
;     const int kb = item / nblk, nb = item - kb * nblk, k0 = 64 * kb, n0 = 32 * nb;
;     const int L = (n0 & ~255) + 64 * ((n0 >> 5) & 3) + 32 * ((n0 >> 7) & 1);
;     const int src0 = mapmode ? ((L >> 5) & 1) * DFF + 128 * (L >> 8) + 32 * ((L >> 6) & 3) : L;
;     f32x4 v[8];
; #pragma unroll
;     for (int i = 0; i < 8; ++i) { const int kk = 8 * i + (lane >> 3); v[i] = __builtin_nontemporal_load((const f32x4*)(W + (size_t)(k0 + kk) * ldw + src0 + 4 * (lane & 7))); }
; #pragma unroll
;     for (int i = 0; i < 8; ++i) { const int kk = 8 * i + (lane >> 3); f32x4 w = v[i]; if (ksc) w *= ksc[k0 + kk];
;         LAS float* d = scr + kk * 33 + 4 * (lane & 7); d[0] = w[0]; d[1] = w[1]; d[2] = w[2]; d[3] = w[3]; }
;     asm volatile("s_waitcnt lgkmcnt(0)" ::: "memory");
;     const int c = lane & 7;
; #pragma unroll
;     for (int j = 0; j < 4; ++j) { const int n = (lane >> 3) + 8 * j; const LAS float* s = scr + (8 * c) * 33 + n;
;         u32x4 o; o.x = cvtpk(s[0 * 33], s[1 * 33]); o.y = cvtpk(s[2 * 33], s[3 * 33]); o.z = cvtpk(s[4 * 33], s[5 * 33]); o.w = cvtpk(s[6 * 33], s[7 * 33]);
;         *(u32x4*)(WT + (size_t)(n0 + n) * K + k0 + 8 * c) = o; }
;     asm volatile("s_waitcnt lgkmcnt(0)" ::: "memory");
; }
.LBB0_549:
	s_andn2_b64 vcc, exec, s[4:5]
	s_cbranch_vccnz .LBB0_551
	s_mov_b64 s[4:5], s[0:1]
	s_load_dwordx2 s[4:5], s[4:5], 0xa8
	s_add_i32 s22, s30, s55
	s_and_b32 s23, s22, 0x3e0
	s_and_b32 s25, s33, 32
	s_and_b32 s22, s22, 0x300
	s_and_b32 s24, s35, 0xc0
	s_or_b32 s22, s25, s22
	s_and_b32 s6, s37, 0x3c0
	s_or_b32 s22, s22, s24
	s_addk_i32 s6, 0xff00
	s_lshl_b32 s22, s22, 2
	s_waitcnt lgkmcnt(0)
	s_add_u32 s4, s4, s22
	v_or_b32_e32 v4, s6, v1
	s_addc_u32 s5, s5, 0
	v_lshl_add_u64 v[2:3], s[4:5], 0, v[38:39]
	v_lshlrev_b32_e32 v4, 10, v4
	v_mov_b32_e32 v5, v39
	v_lshl_add_u64 v[30:31], v[4:5], 2, v[2:3]
	v_add_co_u32_e32 v6, vcc, s44, v30
	s_mov_b64 s[20:21], s[0:1]
	s_nop 0
	v_addc_co_u32_e32 v7, vcc, 0, v31, vcc
	v_add_co_u32_e32 v10, vcc, s45, v30
	global_load_dwordx4 v[2:5], v[30:31], off nt
	s_nop 0
	global_load_dwordx4 v[6:9], v[6:7], off nt
	v_addc_co_u32_e32 v11, vcc, 0, v31, vcc
	v_add_co_u32_e32 v14, vcc, s46, v30
	v_mov_b32_e32 v41, v39
	s_nop 0
	v_addc_co_u32_e32 v15, vcc, 0, v31, vcc
	v_add_co_u32_e32 v18, vcc, s47, v30
	global_load_dwordx4 v[10:13], v[10:11], off nt
	s_nop 0
	global_load_dwordx4 v[14:17], v[14:15], off nt
	v_addc_co_u32_e32 v19, vcc, 0, v31, vcc
	v_add_co_u32_e32 v22, vcc, s48, v30
	v_or_b32_e32 v34, s23, v1
	s_nop 0
	v_addc_co_u32_e32 v23, vcc, 0, v31, vcc
	global_load_dwordx4 v[18:21], v[18:19], off nt
	s_nop 0
	global_load_dwordx4 v[22:25], v[22:23], off nt
	v_add_co_u32_e32 v26, vcc, s49, v30
	s_load_dwordx2 s[4:5], s[20:21], 0xf0
	s_nop 0
	v_addc_co_u32_e32 v27, vcc, 0, v31, vcc
	global_load_dwordx4 v[26:29], v[26:27], off nt
	v_add_co_u32_e32 v30, vcc, s50, v30
	s_lshl_b64 s[20:21], s[6:7], 1
	s_nop 0
	v_addc_co_u32_e32 v31, vcc, 0, v31, vcc
	global_load_dwordx4 v[30:33], v[30:31], off nt
	s_waitcnt lgkmcnt(0)
	s_add_u32 s4, s4, s20
	s_addc_u32 s5, s5, s21
	v_lshl_add_u64 v[36:37], s[4:5], 0, v[40:41]
	v_mov_b32_e32 v35, v39
	v_lshlrev_b32_e32 v34, 10, v34
	v_lshl_add_u64 v[36:37], v[36:37], 0, s[16:17]
	s_waitcnt vmcnt(4)
	ds_write2_b32 v51, v2, v3 offset1:1
	ds_write2_b32 v51, v4, v5 offset0:2 offset1:3
	ds_write2_b32 v52, v6, v7 offset1:1
	ds_write2_b32 v53, v8, v9 offset1:1
	ds_write2_b32 v54, v10, v11 offset1:1
	ds_write2_b32 v55, v12, v13 offset1:1
	ds_write2_b32 v56, v14, v15 offset1:1
	ds_write2_b32 v57, v16, v17 offset1:1
	s_waitcnt vmcnt(3)
	ds_write2_b32 v58, v18, v19 offset1:1
	ds_write2_b32 v59, v20, v21 offset1:1
	s_waitcnt vmcnt(2)
	ds_write2_b32 v60, v22, v23 offset1:1
	ds_write2_b32 v61, v24, v25 offset1:1
	s_waitcnt vmcnt(1)
	ds_write2_b32 v62, v26, v27 offset1:1
	ds_write2_b32 v63, v28, v29 offset1:1
	s_waitcnt vmcnt(0)
	ds_write2_b32 v64, v30, v31 offset1:1
	ds_write2_b32 v65, v32, v33 offset1:1
	s_waitcnt lgkmcnt(0)
	ds_read2_b32 v[6:7], v49 offset0:33 offset1:41
	ds_read2_b32 v[8:9], v49 offset1:8
	ds_read2_b32 v[10:11], v49 offset0:66 offset1:74
	ds_read2_b32 v[12:13], v49 offset0:99 offset1:107
	ds_read2_b32 v[14:15], v49 offset0:132 offset1:140
	ds_read2_b32 v[16:17], v49 offset0:165 offset1:173
	ds_read2_b32 v[18:19], v49 offset0:198 offset1:206
	ds_read2_b32 v[20:21], v49 offset0:231 offset1:239
	v_lshl_add_u64 v[22:23], v[36:37], 0, v[34:35]
	s_waitcnt lgkmcnt(6)
	v_cvt_pk_bf16_f32 v2, v8, v6
	s_waitcnt lgkmcnt(4)
	v_cvt_pk_bf16_f32 v3, v10, v12
	s_waitcnt lgkmcnt(2)
	v_cvt_pk_bf16_f32 v4, v14, v16
	s_waitcnt lgkmcnt(0)
	v_cvt_pk_bf16_f32 v5, v18, v20
	global_store_dwordx4 v[22:23], v[2:5], off
	v_cvt_pk_bf16_f32 v6, v9, v7
	v_cvt_pk_bf16_f32 v7, v11, v13
	v_cvt_pk_bf16_f32 v8, v15, v17
	v_cvt_pk_bf16_f32 v9, v19, v21
	v_or_b32_e32 v2, s23, v46
	ds_read2_b32 v[10:11], v49 offset0:49 offset1:57
	ds_read2_b32 v[12:13], v49 offset0:16 offset1:24
	ds_read2_b32 v[14:15], v49 offset0:82 offset1:90
	ds_read2_b32 v[16:17], v49 offset0:115 offset1:123
	ds_read2_b32 v[18:19], v49 offset0:148 offset1:156
	ds_read2_b32 v[20:21], v49 offset0:181 offset1:189
	ds_read2_b32 v[22:23], v49 offset0:214 offset1:222
	ds_read2_b32 v[24:25], v49 offset0:247 offset1:255
	v_lshlrev_b32_e32 v2, 10, v2
	v_mov_b32_e32 v3, v39
	v_lshl_add_u64 v[2:3], v[36:37], 0, v[2:3]
	global_store_dwordx4 v[2:3], v[6:9], off
	s_waitcnt lgkmcnt(6)
	v_cvt_pk_bf16_f32 v2, v12, v10
	s_waitcnt lgkmcnt(4)
	v_cvt_pk_bf16_f32 v3, v14, v16
	v_or_b32_e32 v6, s23, v47
	v_lshlrev_b32_e32 v6, 10, v6
	v_mov_b32_e32 v7, v39
	s_waitcnt lgkmcnt(2)
	v_cvt_pk_bf16_f32 v4, v18, v20
	s_waitcnt lgkmcnt(0)
	v_cvt_pk_bf16_f32 v5, v22, v24
	v_lshl_add_u64 v[6:7], v[36:37], 0, v[6:7]
	global_store_dwordx4 v[6:7], v[2:5], off
	v_or_b32_e32 v6, s23, v48
	v_lshlrev_b32_e32 v6, 10, v6
	v_mov_b32_e32 v7, v39
	v_cvt_pk_bf16_f32 v2, v13, v11
	v_cvt_pk_bf16_f32 v3, v15, v17
	v_cvt_pk_bf16_f32 v4, v19, v21
	v_cvt_pk_bf16_f32 v5, v23, v25
	v_lshl_add_u64 v[6:7], v[36:37], 0, v[6:7]
	global_store_dwordx4 v[6:7], v[2:5], off
	s_waitcnt lgkmcnt(0)
